# P0 w_in transpose/convert hand-written, each wave converts 4 adjacent items (512 B contiguous per row), all loads up front
# speedup vs baseline: 1.0073x; 1.0073x over previous
.LBB0_7:
	v_writelane_b32 v242, s4, 11
	s_load_dwordx16 s[4:19], s[0:1], 0x40
	s_lshr_b32 s1, s3, 6
	s_lshl_b32 s0, s2, 3
	s_add_i32 s56, s1, s0
	s_lshl_b32 s64, s74, 3
	s_waitcnt lgkmcnt(0)
	v_writelane_b32 v242, s4, 12
	v_and_b32_e32 v142, 63, v143
	s_nop 0
	v_writelane_b32 v242, s5, 13
	v_writelane_b32 v242, s6, 14
	v_writelane_b32 v242, s7, 15
	v_writelane_b32 v242, s8, 16
	v_writelane_b32 v242, s9, 17
	v_writelane_b32 v242, s10, 18
	v_writelane_b32 v242, s11, 19
	v_writelane_b32 v242, s12, 20
	v_writelane_b32 v242, s13, 21
	v_writelane_b32 v242, s14, 22
	v_writelane_b32 v242, s15, 23
	v_writelane_b32 v242, s16, 24
	v_writelane_b32 v242, s17, 25
	v_writelane_b32 v242, s18, 26
	v_writelane_b32 v242, s19, 27
	s_add_u32 s6, s70, 0x100000
	s_addc_u32 s7, s71, 0
	s_lshl_b32 s0, s1, 14
	v_writelane_b32 v242, s1, 28
	s_add_i32 s0, s0, 0
	v_writelane_b32 v242, s0, 29
	v_writelane_b32 v242, s65, 30
	v_writelane_b32 v242, s36, 31
	s_cmp_lt_i32 s72, 1
	s_cselect_b64 s[0:1], -1, 0
	v_writelane_b32 v242, s37, 32
	v_writelane_b32 v242, s38, 33
	v_writelane_b32 v242, s39, 34
	v_writelane_b32 v242, s40, 35
	v_writelane_b32 v242, s41, 36
	v_writelane_b32 v242, s42, 37
	v_writelane_b32 v242, s43, 38
	v_writelane_b32 v242, s44, 39
	v_writelane_b32 v242, s45, 40
	v_writelane_b32 v242, s46, 41
	s_cmp_gt_i32 s73, 0
	v_writelane_b32 v242, s47, 42
	s_cselect_b64 s[4:5], -1, 0
	v_writelane_b32 v242, s48, 43
	s_and_b64 s[4:5], s[0:1], s[4:5]
	v_writelane_b32 v242, s49, 44
	s_andn2_b64 vcc, exec, s[4:5]
	v_writelane_b32 v242, s50, 45
	v_writelane_b32 v242, s51, 46
	s_cbranch_vccnz .LBB0_22
	v_lshrrev_b32_e32 v2, 3, v142
	v_and_b32_e32 v3, 7, v142
	s_lshr_b32 s3, s56, 6
	s_and_b32 s8, s56, 63
	s_lshl_b32 s8, s8, 2
	v_readlane_b32 s10, v242, 14
	v_readlane_b32 s11, v242, 15
	v_readlane_b32 s9, v242, 29
	v_lshlrev_b32_e32 v6, 15, v2
	v_lshlrev_b32_e32 v8, 4, v3
	v_mov_b32_e32 v9, 0
	v_add_u32_e32 v6, v6, v8
	s_lshl_b32 s0, s8, 7
	s_lshl_b32 s12, s3, 21
	s_add_u32 s0, s0, s12
	s_add_u32 s0, s10, s0
	s_addc_u32 s1, s11, 0
	global_load_dwordx4 v[100:103], v6, s[0:1]
	global_load_dwordx4 v[132:135], v6, s[0:1] offset:128
	global_load_dwordx4 v[168:171], v6, s[0:1] offset:256
	global_load_dwordx4 v[200:203], v6, s[0:1] offset:384
	s_add_u32 s14, s0, 0x40000
	s_addc_u32 s15, s1, 0
	global_load_dwordx4 v[104:107], v6, s[14:15]
	global_load_dwordx4 v[136:139], v6, s[14:15] offset:128
	global_load_dwordx4 v[172:175], v6, s[14:15] offset:256
	global_load_dwordx4 v[204:207], v6, s[14:15] offset:384
	s_add_u32 s0, s14, 0x40000
	s_addc_u32 s1, s15, 0
	global_load_dwordx4 v[108:111], v6, s[0:1]
	global_load_dwordx4 v[144:147], v6, s[0:1] offset:128
	global_load_dwordx4 v[176:179], v6, s[0:1] offset:256
	global_load_dwordx4 v[208:211], v6, s[0:1] offset:384
	s_add_u32 s14, s0, 0x40000
	s_addc_u32 s15, s1, 0
	global_load_dwordx4 v[112:115], v6, s[14:15]
	global_load_dwordx4 v[148:151], v6, s[14:15] offset:128
	global_load_dwordx4 v[180:183], v6, s[14:15] offset:256
	global_load_dwordx4 v[212:215], v6, s[14:15] offset:384
	s_add_u32 s0, s14, 0x40000
	s_addc_u32 s1, s15, 0
	global_load_dwordx4 v[116:119], v6, s[0:1]
	global_load_dwordx4 v[152:155], v6, s[0:1] offset:128
	global_load_dwordx4 v[184:187], v6, s[0:1] offset:256
	global_load_dwordx4 v[216:219], v6, s[0:1] offset:384
	s_add_u32 s14, s0, 0x40000
	s_addc_u32 s15, s1, 0
	global_load_dwordx4 v[120:123], v6, s[14:15]
	global_load_dwordx4 v[156:159], v6, s[14:15] offset:128
	global_load_dwordx4 v[188:191], v6, s[14:15] offset:256
	global_load_dwordx4 v[220:223], v6, s[14:15] offset:384
	s_add_u32 s0, s14, 0x40000
	s_addc_u32 s1, s15, 0
	global_load_dwordx4 v[124:127], v6, s[0:1]
	global_load_dwordx4 v[160:163], v6, s[0:1] offset:128
	global_load_dwordx4 v[192:195], v6, s[0:1] offset:256
	global_load_dwordx4 v[224:227], v6, s[0:1] offset:384
	s_add_u32 s14, s0, 0x40000
	s_addc_u32 s15, s1, 0
	global_load_dwordx4 v[128:131], v6, s[14:15]
	global_load_dwordx4 v[164:167], v6, s[14:15] offset:128
	global_load_dwordx4 v[196:199], v6, s[14:15] offset:256
	global_load_dwordx4 v[228:231], v6, s[14:15] offset:384
	v_mul_u32_u24_e32 v10, 0x84, v2
	v_lshl_add_u32 v10, v3, 4, v10
	v_add_u32_e32 v10, s9, v10
	v_add_u32_e32 v11, 0x420, v10
	v_add_u32_e32 v12, 0x840, v10
	v_add_u32_e32 v13, 0xc60, v10
	v_add_u32_e32 v14, 0x1080, v10
	v_add_u32_e32 v15, 0x14a0, v10
	v_add_u32_e32 v16, 0x18c0, v10
	v_add_u32_e32 v17, 0x1ce0, v10
	v_mul_u32_u24_e32 v18, 0x420, v3
	v_lshl_add_u32 v18, v2, 2, v18
	v_add_u32_e32 v18, s9, v18
	s_lshl_b32 s16, s8, 5
	v_add_u32_e32 v28, s16, v2
	v_mov_b32_e32 v29, 0
	v_lshlrev_b64 v[28:29], 12, v[28:29]
	s_lshl_b32 s16, s3, 7
	s_add_u32 s16, s6, s16
	s_addc_u32 s17, s7, 0
	v_lshl_add_u64 v[20:21], v[28:29], 0, s[16:17]
	v_lshl_add_u64 v[20:21], v[20:21], 0, v[8:9]
	s_mov_b64 s[18:19], 0x8000
	v_lshl_add_u64 v[22:23], v[20:21], 0, s[18:19]
	v_lshl_add_u64 v[24:25], v[22:23], 0, s[18:19]
	v_lshl_add_u64 v[26:27], v[24:25], 0, s[18:19]
	s_mov_b64 s[18:19], 0x20000
	s_waitcnt vmcnt(31)
	ds_write2_b32 v10, v100, v101 offset1:1
	ds_write2_b32 v10, v102, v103 offset0:2 offset1:3
	s_waitcnt vmcnt(27)
	ds_write2_b32 v11, v104, v105 offset1:1
	ds_write2_b32 v11, v106, v107 offset0:2 offset1:3
	s_waitcnt vmcnt(23)
	ds_write2_b32 v12, v108, v109 offset1:1
	ds_write2_b32 v12, v110, v111 offset0:2 offset1:3
	s_waitcnt vmcnt(19)
	ds_write2_b32 v13, v112, v113 offset1:1
	ds_write2_b32 v13, v114, v115 offset0:2 offset1:3
	s_waitcnt vmcnt(15)
	ds_write2_b32 v14, v116, v117 offset1:1
	ds_write2_b32 v14, v118, v119 offset0:2 offset1:3
	s_waitcnt vmcnt(11)
	ds_write2_b32 v15, v120, v121 offset1:1
	ds_write2_b32 v15, v122, v123 offset0:2 offset1:3
	s_waitcnt vmcnt(7)
	ds_write2_b32 v16, v124, v125 offset1:1
	ds_write2_b32 v16, v126, v127 offset0:2 offset1:3
	s_waitcnt vmcnt(3)
	ds_write2_b32 v17, v128, v129 offset1:1
	ds_write2_b32 v17, v130, v131 offset0:2 offset1:3
	s_waitcnt lgkmcnt(0)
	ds_read2_b32 v[44:45], v18 offset0:0 offset1:8
	ds_read2_b32 v[46:47], v18 offset0:33 offset1:41
	ds_read2_b32 v[48:49], v18 offset0:66 offset1:74
	ds_read2_b32 v[50:51], v18 offset0:99 offset1:107
	ds_read2_b32 v[52:53], v18 offset0:132 offset1:140
	ds_read2_b32 v[54:55], v18 offset0:165 offset1:173
	ds_read2_b32 v[56:57], v18 offset0:198 offset1:206
	ds_read2_b32 v[58:59], v18 offset0:231 offset1:239
	s_waitcnt lgkmcnt(0)
	v_cvt_pk_bf16_f32 v76, v44, v46
	v_cvt_pk_bf16_f32 v77, v48, v50
	v_cvt_pk_bf16_f32 v78, v52, v54
	v_cvt_pk_bf16_f32 v79, v56, v58
	global_store_dwordx4 v[20:21], v[76:79], off
	v_cvt_pk_bf16_f32 v80, v45, v47
	v_cvt_pk_bf16_f32 v81, v49, v51
	v_cvt_pk_bf16_f32 v82, v53, v55
	v_cvt_pk_bf16_f32 v83, v57, v59
	global_store_dwordx4 v[22:23], v[80:83], off
	ds_read2_b32 v[60:61], v18 offset0:16 offset1:24
	ds_read2_b32 v[62:63], v18 offset0:49 offset1:57
	ds_read2_b32 v[64:65], v18 offset0:82 offset1:90
	ds_read2_b32 v[66:67], v18 offset0:115 offset1:123
	ds_read2_b32 v[68:69], v18 offset0:148 offset1:156
	ds_read2_b32 v[70:71], v18 offset0:181 offset1:189
	ds_read2_b32 v[72:73], v18 offset0:214 offset1:222
	ds_read2_b32 v[74:75], v18 offset0:247 offset1:255
	s_waitcnt lgkmcnt(0)
	v_cvt_pk_bf16_f32 v84, v60, v62
	v_cvt_pk_bf16_f32 v85, v64, v66
	v_cvt_pk_bf16_f32 v86, v68, v70
	v_cvt_pk_bf16_f32 v87, v72, v74
	global_store_dwordx4 v[24:25], v[84:87], off
	v_cvt_pk_bf16_f32 v88, v61, v63
	v_cvt_pk_bf16_f32 v89, v65, v67
	v_cvt_pk_bf16_f32 v90, v69, v71
	v_cvt_pk_bf16_f32 v91, v73, v75
	global_store_dwordx4 v[26:27], v[88:91], off
	v_lshl_add_u64 v[20:21], v[20:21], 0, s[18:19]
	v_lshl_add_u64 v[22:23], v[22:23], 0, s[18:19]
	v_lshl_add_u64 v[24:25], v[24:25], 0, s[18:19]
	v_lshl_add_u64 v[26:27], v[26:27], 0, s[18:19]
	s_waitcnt vmcnt(34)
	ds_write2_b32 v10, v132, v133 offset1:1
	ds_write2_b32 v10, v134, v135 offset0:2 offset1:3
	s_waitcnt vmcnt(30)
	ds_write2_b32 v11, v136, v137 offset1:1
	ds_write2_b32 v11, v138, v139 offset0:2 offset1:3
	s_waitcnt vmcnt(26)
	ds_write2_b32 v12, v144, v145 offset1:1
	ds_write2_b32 v12, v146, v147 offset0:2 offset1:3
	s_waitcnt vmcnt(22)
	ds_write2_b32 v13, v148, v149 offset1:1
	ds_write2_b32 v13, v150, v151 offset0:2 offset1:3
	s_waitcnt vmcnt(18)
	ds_write2_b32 v14, v152, v153 offset1:1
	ds_write2_b32 v14, v154, v155 offset0:2 offset1:3
	s_waitcnt vmcnt(14)
	ds_write2_b32 v15, v156, v157 offset1:1
	ds_write2_b32 v15, v158, v159 offset0:2 offset1:3
	s_waitcnt vmcnt(10)
	ds_write2_b32 v16, v160, v161 offset1:1
	ds_write2_b32 v16, v162, v163 offset0:2 offset1:3
	s_waitcnt vmcnt(6)
	ds_write2_b32 v17, v164, v165 offset1:1
	ds_write2_b32 v17, v166, v167 offset0:2 offset1:3
	s_waitcnt lgkmcnt(0)
	ds_read2_b32 v[44:45], v18 offset0:0 offset1:8
	ds_read2_b32 v[46:47], v18 offset0:33 offset1:41
	ds_read2_b32 v[48:49], v18 offset0:66 offset1:74
	ds_read2_b32 v[50:51], v18 offset0:99 offset1:107
	ds_read2_b32 v[52:53], v18 offset0:132 offset1:140
	ds_read2_b32 v[54:55], v18 offset0:165 offset1:173
	ds_read2_b32 v[56:57], v18 offset0:198 offset1:206
	ds_read2_b32 v[58:59], v18 offset0:231 offset1:239
	s_waitcnt lgkmcnt(0)
	v_cvt_pk_bf16_f32 v76, v44, v46
	v_cvt_pk_bf16_f32 v77, v48, v50
	v_cvt_pk_bf16_f32 v78, v52, v54
	v_cvt_pk_bf16_f32 v79, v56, v58
	global_store_dwordx4 v[20:21], v[76:79], off
	v_cvt_pk_bf16_f32 v80, v45, v47
	v_cvt_pk_bf16_f32 v81, v49, v51
	v_cvt_pk_bf16_f32 v82, v53, v55
	v_cvt_pk_bf16_f32 v83, v57, v59
	global_store_dwordx4 v[22:23], v[80:83], off
	ds_read2_b32 v[60:61], v18 offset0:16 offset1:24
	ds_read2_b32 v[62:63], v18 offset0:49 offset1:57
	ds_read2_b32 v[64:65], v18 offset0:82 offset1:90
	ds_read2_b32 v[66:67], v18 offset0:115 offset1:123
	ds_read2_b32 v[68:69], v18 offset0:148 offset1:156
	ds_read2_b32 v[70:71], v18 offset0:181 offset1:189
	ds_read2_b32 v[72:73], v18 offset0:214 offset1:222
	ds_read2_b32 v[74:75], v18 offset0:247 offset1:255
	s_waitcnt lgkmcnt(0)
	v_cvt_pk_bf16_f32 v84, v60, v62
	v_cvt_pk_bf16_f32 v85, v64, v66
	v_cvt_pk_bf16_f32 v86, v68, v70
	v_cvt_pk_bf16_f32 v87, v72, v74
	global_store_dwordx4 v[24:25], v[84:87], off
	v_cvt_pk_bf16_f32 v88, v61, v63
	v_cvt_pk_bf16_f32 v89, v65, v67
	v_cvt_pk_bf16_f32 v90, v69, v71
	v_cvt_pk_bf16_f32 v91, v73, v75
	global_store_dwordx4 v[26:27], v[88:91], off
	v_lshl_add_u64 v[20:21], v[20:21], 0, s[18:19]
	v_lshl_add_u64 v[22:23], v[22:23], 0, s[18:19]
	v_lshl_add_u64 v[24:25], v[24:25], 0, s[18:19]
	v_lshl_add_u64 v[26:27], v[26:27], 0, s[18:19]
	s_waitcnt vmcnt(37)
	ds_write2_b32 v10, v168, v169 offset1:1
	ds_write2_b32 v10, v170, v171 offset0:2 offset1:3
	s_waitcnt vmcnt(33)
	ds_write2_b32 v11, v172, v173 offset1:1
	ds_write2_b32 v11, v174, v175 offset0:2 offset1:3
	s_waitcnt vmcnt(29)
	ds_write2_b32 v12, v176, v177 offset1:1
	ds_write2_b32 v12, v178, v179 offset0:2 offset1:3
	s_waitcnt vmcnt(25)
	ds_write2_b32 v13, v180, v181 offset1:1
	ds_write2_b32 v13, v182, v183 offset0:2 offset1:3
	s_waitcnt vmcnt(21)
	ds_write2_b32 v14, v184, v185 offset1:1
	ds_write2_b32 v14, v186, v187 offset0:2 offset1:3
	s_waitcnt vmcnt(17)
	ds_write2_b32 v15, v188, v189 offset1:1
	ds_write2_b32 v15, v190, v191 offset0:2 offset1:3
	s_waitcnt vmcnt(13)
	ds_write2_b32 v16, v192, v193 offset1:1
	ds_write2_b32 v16, v194, v195 offset0:2 offset1:3
	s_waitcnt vmcnt(9)
	ds_write2_b32 v17, v196, v197 offset1:1
	ds_write2_b32 v17, v198, v199 offset0:2 offset1:3
	s_waitcnt lgkmcnt(0)
	ds_read2_b32 v[44:45], v18 offset0:0 offset1:8
	ds_read2_b32 v[46:47], v18 offset0:33 offset1:41
	ds_read2_b32 v[48:49], v18 offset0:66 offset1:74
	ds_read2_b32 v[50:51], v18 offset0:99 offset1:107
	ds_read2_b32 v[52:53], v18 offset0:132 offset1:140
	ds_read2_b32 v[54:55], v18 offset0:165 offset1:173
	ds_read2_b32 v[56:57], v18 offset0:198 offset1:206
	ds_read2_b32 v[58:59], v18 offset0:231 offset1:239
	s_waitcnt lgkmcnt(0)
	v_cvt_pk_bf16_f32 v76, v44, v46
	v_cvt_pk_bf16_f32 v77, v48, v50
	v_cvt_pk_bf16_f32 v78, v52, v54
	v_cvt_pk_bf16_f32 v79, v56, v58
	global_store_dwordx4 v[20:21], v[76:79], off
	v_cvt_pk_bf16_f32 v80, v45, v47
	v_cvt_pk_bf16_f32 v81, v49, v51
	v_cvt_pk_bf16_f32 v82, v53, v55
	v_cvt_pk_bf16_f32 v83, v57, v59
	global_store_dwordx4 v[22:23], v[80:83], off
	ds_read2_b32 v[60:61], v18 offset0:16 offset1:24
	ds_read2_b32 v[62:63], v18 offset0:49 offset1:57
	ds_read2_b32 v[64:65], v18 offset0:82 offset1:90
	ds_read2_b32 v[66:67], v18 offset0:115 offset1:123
	ds_read2_b32 v[68:69], v18 offset0:148 offset1:156
	ds_read2_b32 v[70:71], v18 offset0:181 offset1:189
	ds_read2_b32 v[72:73], v18 offset0:214 offset1:222
	ds_read2_b32 v[74:75], v18 offset0:247 offset1:255
	s_waitcnt lgkmcnt(0)
	v_cvt_pk_bf16_f32 v84, v60, v62
	v_cvt_pk_bf16_f32 v85, v64, v66
	v_cvt_pk_bf16_f32 v86, v68, v70
	v_cvt_pk_bf16_f32 v87, v72, v74
	global_store_dwordx4 v[24:25], v[84:87], off
	v_cvt_pk_bf16_f32 v88, v61, v63
	v_cvt_pk_bf16_f32 v89, v65, v67
	v_cvt_pk_bf16_f32 v90, v69, v71
	v_cvt_pk_bf16_f32 v91, v73, v75
	global_store_dwordx4 v[26:27], v[88:91], off
	v_lshl_add_u64 v[20:21], v[20:21], 0, s[18:19]
	v_lshl_add_u64 v[22:23], v[22:23], 0, s[18:19]
	v_lshl_add_u64 v[24:25], v[24:25], 0, s[18:19]
	v_lshl_add_u64 v[26:27], v[26:27], 0, s[18:19]
	s_waitcnt vmcnt(40)
	ds_write2_b32 v10, v200, v201 offset1:1
	ds_write2_b32 v10, v202, v203 offset0:2 offset1:3
	s_waitcnt vmcnt(36)
	ds_write2_b32 v11, v204, v205 offset1:1
	ds_write2_b32 v11, v206, v207 offset0:2 offset1:3
	s_waitcnt vmcnt(32)
	ds_write2_b32 v12, v208, v209 offset1:1
	ds_write2_b32 v12, v210, v211 offset0:2 offset1:3
	s_waitcnt vmcnt(28)
	ds_write2_b32 v13, v212, v213 offset1:1
	ds_write2_b32 v13, v214, v215 offset0:2 offset1:3
	s_waitcnt vmcnt(24)
	ds_write2_b32 v14, v216, v217 offset1:1
	ds_write2_b32 v14, v218, v219 offset0:2 offset1:3
	s_waitcnt vmcnt(20)
	ds_write2_b32 v15, v220, v221 offset1:1
	ds_write2_b32 v15, v222, v223 offset0:2 offset1:3
	s_waitcnt vmcnt(16)
	ds_write2_b32 v16, v224, v225 offset1:1
	ds_write2_b32 v16, v226, v227 offset0:2 offset1:3
	s_waitcnt vmcnt(12)
	ds_write2_b32 v17, v228, v229 offset1:1
	ds_write2_b32 v17, v230, v231 offset0:2 offset1:3
	s_waitcnt lgkmcnt(0)
	ds_read2_b32 v[44:45], v18 offset0:0 offset1:8
	ds_read2_b32 v[46:47], v18 offset0:33 offset1:41
	ds_read2_b32 v[48:49], v18 offset0:66 offset1:74
	ds_read2_b32 v[50:51], v18 offset0:99 offset1:107
	ds_read2_b32 v[52:53], v18 offset0:132 offset1:140
	ds_read2_b32 v[54:55], v18 offset0:165 offset1:173
	ds_read2_b32 v[56:57], v18 offset0:198 offset1:206
	ds_read2_b32 v[58:59], v18 offset0:231 offset1:239
	s_waitcnt lgkmcnt(0)
	v_cvt_pk_bf16_f32 v76, v44, v46
	v_cvt_pk_bf16_f32 v77, v48, v50
	v_cvt_pk_bf16_f32 v78, v52, v54
	v_cvt_pk_bf16_f32 v79, v56, v58
	global_store_dwordx4 v[20:21], v[76:79], off
	v_cvt_pk_bf16_f32 v80, v45, v47
	v_cvt_pk_bf16_f32 v81, v49, v51
	v_cvt_pk_bf16_f32 v82, v53, v55
	v_cvt_pk_bf16_f32 v83, v57, v59
	global_store_dwordx4 v[22:23], v[80:83], off
	ds_read2_b32 v[60:61], v18 offset0:16 offset1:24
	ds_read2_b32 v[62:63], v18 offset0:49 offset1:57
	ds_read2_b32 v[64:65], v18 offset0:82 offset1:90
	ds_read2_b32 v[66:67], v18 offset0:115 offset1:123
	ds_read2_b32 v[68:69], v18 offset0:148 offset1:156
	ds_read2_b32 v[70:71], v18 offset0:181 offset1:189
	ds_read2_b32 v[72:73], v18 offset0:214 offset1:222
	ds_read2_b32 v[74:75], v18 offset0:247 offset1:255
	s_waitcnt lgkmcnt(0)
	v_cvt_pk_bf16_f32 v84, v60, v62
	v_cvt_pk_bf16_f32 v85, v64, v66
	v_cvt_pk_bf16_f32 v86, v68, v70
	v_cvt_pk_bf16_f32 v87, v72, v74
	global_store_dwordx4 v[24:25], v[84:87], off
	v_cvt_pk_bf16_f32 v88, v61, v63
	v_cvt_pk_bf16_f32 v89, v65, v67
	v_cvt_pk_bf16_f32 v90, v69, v71
	v_cvt_pk_bf16_f32 v91, v73, v75
	global_store_dwordx4 v[26:27], v[88:91], off
